# phase 0 W_in transpose tile: LDS tile double-buffered by tile parity so the second workgroup barrier of each tile is dropped
# speedup vs baseline: 1.0035x; 1.0035x over previous
; template <int MODE>
; DI void transpose_tile(const float* __restrict__ W, int K, int Nsrc, bf16_t* __restrict__ WT, int ldo, const float* __restrict__ gain, int k0, int n0,
;                        unsigned char* smem, int tid) {
;     ...
;     __syncthreads();
; #pragma unroll
;     for (int i = 0; i < 2; ++i) {
;         const int c = tid + 256 * i, nn = c >> 3, kc = c & 7;
;         const unsigned* s = (const unsigned*)(t + nn * 66 + kc * 8);
;         u32x4 o = {s[0], s[1], s[2], s[3]};
;         *(u32x4*)(WT + (size_t)(n0 + nn) * ldo + k0 + kc * 8) = o;
;     }
;     __syncthreads();
.LBB0_26:
	s_ashr_i32 s21, s20, 31
	v_lshlrev_b32_e32 v1, 4, v6
	s_lshl_b64 s[0:1], s[20:21], 1
	v_and_b32_e32 v4, 0x70, v1
	s_add_u32 s0, s25, s0
	v_add_u32_e32 v12, s98, v4
	s_addc_u32 s1, s26, s1
	v_ashrrev_i32_e32 v1, 3, v6
	v_lshl_add_u64 v[16:17], s[0:1], 0, v[4:5]
	v_mad_u64_u32 v[10:11], s[0:1], v1, s27, v[12:13]
	v_add_u32_e32 v1, s36, v1
	v_mad_i64_i32 v[18:19], s[0:1], v1, s28, v[16:17]
	v_add_u32_e32 v1, 0x100, v6
	v_ashrrev_i32_e32 v1, 3, v1
	v_mad_u64_u32 v[6:7], s[0:1], v1, s27, v[12:13]
	s_waitcnt lgkmcnt(0)
	s_barrier
	ds_read2_b32 v[8:9], v10 offset1:1
	ds_read2_b32 v[10:11], v10 offset0:2 offset1:3
	ds_read2_b32 v[12:13], v6 offset1:1
	ds_read2_b32 v[14:15], v6 offset0:2 offset1:3
	v_add_u32_e32 v1, s36, v1
	v_mad_i64_i32 v[6:7], s[0:1], v1, s28, v[16:17]
	s_waitcnt lgkmcnt(2)
	global_store_dwordx4 v[18:19], v[8:11], off
	s_waitcnt lgkmcnt(0)
	global_store_dwordx4 v[6:7], v[12:15], off

; DI bf16_t f2bf(float a) { return (bf16_t)(pk2(a, 0.f) & 0xffffu); }
; DI int win_src_col(int n) {
;     if (n < 832) return n;
;     if (n < 848) return 4928 + (n - 832);
;     if (n < 896) return -1;
;     if (n < 1920) return 832 + (n - 896);
;     if (n < 2944) return 4944 + (n - 1920);
;     if (n < 6016) return 1856 + (n - 2944);
;     return -1;
; }
; template <int MODE>
; DI void transpose_tile(const float* __restrict__ W, int K, int Nsrc, bf16_t* __restrict__ WT, int ldo, const float* __restrict__ gain, int k0, int n0,
;                        unsigned char* smem, int tid) {
;     bf16_t* t = (bf16_t*)smem;
; #pragma unroll 4
;     for (int i = 0; i < 16; ++i) {
;         const int e = tid + 256 * i, kk = e >> 6, nn = e & 63;
;         const int src = MODE == 0 ? win_src_col(n0 + nn) : (n0 + nn);
;         float v = src >= 0 ? W[(size_t)(k0 + kk) * Nsrc + src] : 0.f;
;         if (gain) v *= gain[k0 + kk];
;         t[nn * 66 + kk] = f2bf(v);
;     }
.LBB0_61:
	s_bfe_u32 s98, s35, 0x10009
	s_mulk_i32 s98, 0x2200
	s_add_i32 s98, s98, s10
	s_mul_hi_i32 s0, s35, 0x2aaaaaab
	s_lshr_b32 s1, s0, 31
	s_ashr_i32 s0, s0, 4
	s_add_i32 s0, s0, s1
	s_lshl_b32 s20, s0, 6
	s_mulk_i32 s0, 0x60
	s_sub_i32 s0, s35, s0
	s_lshl_b32 s36, s0, 6
	v_and_b32_e32 v1, 63, v6
	v_or_b32_e32 v3, s36, v1
	s_cmpk_lt_u32 s36, 0x380
	v_or_b32_e32 v4, 0x1000, v3
	v_cmp_gt_u32_e32 vcc, s31, v3
	v_add_u32_e32 v9, 0xfffffbc0, v3
	v_add_u32_e32 v8, 0xbd0, v3
	v_cndmask_b32_e32 v4, -1, v4, vcc
	s_cselect_b64 vcc, -1, 0
	s_cmpk_lt_u32 s36, 0x780
	s_cselect_b64 s[0:1], -1, 0
	s_cmpk_lt_u32 s36, 0xb80
	s_cselect_b64 s[4:5], -1, 0
	s_cmpk_lt_u32 s36, 0x1780
	s_cselect_b64 s[6:7], -1, 0
	v_cndmask_b32_e64 v9, -1, v9, s[6:7]
	v_subrev_u32_e32 v7, 64, v3
	v_cndmask_b32_e64 v8, v9, v8, s[4:5]
	v_cndmask_b32_e64 v7, v8, v7, s[0:1]
	v_cndmask_b32_e32 v4, v7, v4, vcc
	v_cmp_gt_i32_e32 vcc, s30, v3
	s_mov_b32 s4, 0
	s_nop 0
	v_cndmask_b32_e32 v4, v4, v3, vcc
	v_mov_b32_e32 v3, s98
	v_cmp_lt_i32_e32 vcc, -1, v4
	v_lshl_add_u64 v[8:9], v[4:5], 2, s[46:47]
	v_mad_u32_u24 v1, v1, s27, v3
	v_lshrrev_b32_e32 v3, 6, v6
	v_add_u32_e32 v7, s20, v3
	v_mad_i64_i32 v[10:11], s[6:7], v7, s34, v[8:9]
	v_lshl_add_u32 v1, v3, 1, v1
	s_mov_b32 s0, 0x17500
	s_mov_b32 s1, 0
	v_mov_b32_e32 v12, 0
	v_mov_b32_e32 v13, 0
	v_mov_b32_e32 v14, 0
	v_mov_b32_e32 v15, 0
	v_mov_b32_e32 v16, 0
	v_mov_b32_e32 v17, 0
	v_mov_b32_e32 v18, 0
	v_mov_b32_e32 v19, 0
	v_mov_b32_e32 v20, 0
	v_mov_b32_e32 v21, 0
	v_mov_b32_e32 v22, 0
	v_mov_b32_e32 v23, 0
	v_mov_b32_e32 v24, 0
	v_mov_b32_e32 v25, 0
	v_mov_b32_e32 v26, 0
	v_mov_b32_e32 v27, 0
	s_and_saveexec_b64 s[4:5], vcc
	global_load_dword v12, v[10:11], off
	v_lshl_add_u64 v[10:11], v[10:11], 0, s[0:1]
	global_load_dword v13, v[10:11], off
	v_lshl_add_u64 v[10:11], v[10:11], 0, s[0:1]
	global_load_dword v14, v[10:11], off
	v_lshl_add_u64 v[10:11], v[10:11], 0, s[0:1]
	global_load_dword v15, v[10:11], off
	v_lshl_add_u64 v[10:11], v[10:11], 0, s[0:1]
	global_load_dword v16, v[10:11], off
	v_lshl_add_u64 v[10:11], v[10:11], 0, s[0:1]
	global_load_dword v17, v[10:11], off
	v_lshl_add_u64 v[10:11], v[10:11], 0, s[0:1]
	global_load_dword v18, v[10:11], off
	v_lshl_add_u64 v[10:11], v[10:11], 0, s[0:1]
	global_load_dword v19, v[10:11], off
	v_lshl_add_u64 v[10:11], v[10:11], 0, s[0:1]
	global_load_dword v20, v[10:11], off
	v_lshl_add_u64 v[10:11], v[10:11], 0, s[0:1]
	global_load_dword v21, v[10:11], off
	v_lshl_add_u64 v[10:11], v[10:11], 0, s[0:1]
	global_load_dword v22, v[10:11], off
	v_lshl_add_u64 v[10:11], v[10:11], 0, s[0:1]
	global_load_dword v23, v[10:11], off
	v_lshl_add_u64 v[10:11], v[10:11], 0, s[0:1]
	global_load_dword v24, v[10:11], off
	v_lshl_add_u64 v[10:11], v[10:11], 0, s[0:1]
	global_load_dword v25, v[10:11], off
	v_lshl_add_u64 v[10:11], v[10:11], 0, s[0:1]
	global_load_dword v26, v[10:11], off
	v_lshl_add_u64 v[10:11], v[10:11], 0, s[0:1]
	global_load_dword v27, v[10:11], off
	s_or_b64 exec, exec, s[4:5]
	s_waitcnt vmcnt(14)
	v_cvt_pk_bf16_f32 v12, v12, v13
	ds_write_b16 v1, v12
	ds_write_b16_d16_hi v1, v12 offset:8
	s_waitcnt vmcnt(12)
	v_cvt_pk_bf16_f32 v14, v14, v15
	ds_write_b16 v1, v14 offset:16
	ds_write_b16_d16_hi v1, v14 offset:24
	s_waitcnt vmcnt(10)
	v_cvt_pk_bf16_f32 v16, v16, v17
	ds_write_b16 v1, v16 offset:32
	ds_write_b16_d16_hi v1, v16 offset:40
	s_waitcnt vmcnt(8)
	v_cvt_pk_bf16_f32 v18, v18, v19
	ds_write_b16 v1, v18 offset:48
	ds_write_b16_d16_hi v1, v18 offset:56
	s_waitcnt vmcnt(6)
	v_cvt_pk_bf16_f32 v20, v20, v21
	ds_write_b16 v1, v20 offset:64
	ds_write_b16_d16_hi v1, v20 offset:72
	s_waitcnt vmcnt(4)
	v_cvt_pk_bf16_f32 v22, v22, v23
	ds_write_b16 v1, v22 offset:80
	ds_write_b16_d16_hi v1, v22 offset:88
	s_waitcnt vmcnt(2)
	v_cvt_pk_bf16_f32 v24, v24, v25
	ds_write_b16 v1, v24 offset:96
	ds_write_b16_d16_hi v1, v24 offset:104
	s_waitcnt vmcnt(0)
	v_cvt_pk_bf16_f32 v26, v26, v27
	ds_write_b16 v1, v26 offset:112
	ds_write_b16_d16_hi v1, v26 offset:120
	s_branch .LBB0_26
